# combo1 plus: leading barrier of each GEMM compute segment sunk below its first 4 MFMAs (register-only, low priority)
# speedup vs baseline: 1.0100x; 1.0031x over previous
; #define PG8_STAGE(bufoff, gbase, voff) do { _Pragma("unroll") for (int _i = 0; _i < 2; ++_i) \
;         __builtin_amdgcn_global_load_lds((const unsigned*)((const char*)(gbase) + (voff)[_i]), (PG8_LAS unsigned*)(lds + (bufoff) + ldsw + _i * 8192), 16, 0, 0); } while (0)
; #define PG8_LDA(dst, b, h) do { _Pragma("unroll") for (int m = 0; m < 4; ++m) _Pragma("unroll") for (int k = 0; k < 2; ++k) dst[m][k] = *(const PG8_LAS bf16x8*)(lds + PG8_SA(b, h) + aoff + m * 2048 + k * 1024); } while (0)
; #define PG8_LDB(dst, b, h) do { _Pragma("unroll") for (int n = 0; n < 2; ++n) _Pragma("unroll") for (int k = 0; k < 2; ++k) dst[n][k] = *(const PG8_LAS bf16x8*)(lds + PG8_SB(b, h) + boff + n * 2048 + k * 1024); } while (0)
; #define PG8_MMA(ai, bj, At, Bt) do { __builtin_amdgcn_s_setprio(1); _Pragma("unroll") for (int m = 0; m < 4; ++m) _Pragma("unroll") for (int n = 0; n < 2; ++n) _Pragma("unroll") for (int k = 0; k < 2; ++k) \
;         acc[ai][bj][m][n] = __builtin_amdgcn_mfma_f32_16x16x32_bf16(Bt[n][k], At[m][k], acc[ai][bj][m][n], 0, 0, 0); __builtin_amdgcn_s_setprio(0); } while (0)
; #define PG8_WAIT_V(n) asm volatile("s_waitcnt vmcnt(" #n ")" ::: "memory")
; #define PG8_WAIT_L(n) asm volatile("s_waitcnt lgkmcnt(" #n ")" ::: "memory")
; #define PG8_BAR __builtin_amdgcn_s_barrier()
; #define PG8_SCHED __builtin_amdgcn_sched_barrier(0)
; template <class Epi, class Sched, bool ALIGN_EPI = false, bool SP2 = false>
; __device__ __forceinline__ void gemm_phase(PG8_LAS unsigned char* lds, const Gemm g, const Sched& S, const Epi& E) {
;     ...
;             PG8_LDB(B0, 0, 0); PG8_LDB(B1, 0, 1); PG8_SCHED; PG8_LDA(At, 0, 0); PG8_STAGE(PG8_SA(1, 1), a1 + hstep, voffA);
;             PG8_WAIT_V(8); PG8_WAIT_L(0); PG8_BAR; PG8_MMA(0, 0, At, B0); PG8_MMA(0, 1, At, B1); PG8_BAR; PG8_SCHED;
;             PG8_LDA(At, 0, 1); PG8_STAGE(PG8_SB(0, 0), b2, voffB); PG8_STAGE(PG8_SB(0, 1), b2 + hstep, voffB); PG8_STAGE(PG8_SA(0, 0), a2, voffA);
;             PG8_WAIT_V(8); PG8_WAIT_L(0); PG8_BAR; PG8_MMA(1, 0, At, B0); PG8_MMA(1, 1, At, B1); PG8_BAR; PG8_SCHED;
.LBB0_274:
	s_add_u32 s22, s20, 0xfffc0080
	s_addc_u32 s23, s21, -1
	s_add_i32 s39, 0, 0x10000
	s_cmp_eq_u32 s38, 12
	s_cselect_b32 s25, s5, s23
	s_cselect_b32 s24, s13, s22
	v_add_u32_e32 v148, s39, v151
	s_cselect_b32 s23, s11, s37
	s_cselect_b32 s22, s35, s36
	s_add_i32 s45, 0, 0x14000
	ds_read_b128 v[140:143], v148
	ds_read_b128 v[144:147], v148 offset:1024
	ds_read_b128 v[156:159], v148 offset:2048
	ds_read_b128 v[160:163], v148 offset:3072
	v_add_u32_e32 v148, s45, v151
	ds_read_b128 v[164:167], v148
	ds_read_b128 v[168:171], v148 offset:1024
	ds_read_b128 v[182:185], v148 offset:2048
	ds_read_b128 v[186:189], v148 offset:3072
	v_lshl_add_u64 v[148:149], s[20:21], 0, v[136:137]
	s_add_i32 m0, s19, 0xc000
	ds_read_b128 v[190:193], v154
	ds_read_b128 v[194:197], v154 offset:1024
	ds_read_b128 v[198:201], v154 offset:2048
	ds_read_b128 v[202:205], v154 offset:3072
	ds_read_b128 v[228:231], v154 offset:4096
	ds_read_b128 v[236:239], v154 offset:5120
	ds_read_b128 v[240:243], v154 offset:6144
	ds_read_b128 v[244:247], v154 offset:7168
	global_load_lds_dwordx4 v[148:149], off
	v_lshl_add_u64 v[148:149], s[20:21], 0, v[138:139]
	s_add_i32 m0, s19, 0xe000
	s_nop 0
	global_load_lds_dwordx4 v[148:149], off
	s_waitcnt vmcnt(8)
	s_waitcnt lgkmcnt(0)
	v_mfma_f32_16x16x32_bf16 v[124:127], v[140:143], v[190:193], v[124:127]
	v_mfma_f32_16x16x32_bf16 v[120:123], v[156:159], v[190:193], v[120:123]
	v_mfma_f32_16x16x32_bf16 v[108:111], v[140:143], v[198:201], v[108:111]
	v_mfma_f32_16x16x32_bf16 v[104:107], v[156:159], v[198:201], v[104:107]
	s_barrier
	s_setprio 1
	s_waitcnt lgkmcnt(0)
	v_mfma_f32_16x16x32_bf16 v[92:95], v[140:143], v[228:231], v[92:95]
	v_mfma_f32_16x16x32_bf16 v[88:91], v[156:159], v[228:231], v[88:91]
	v_mfma_f32_16x16x32_bf16 v[76:79], v[140:143], v[240:243], v[76:79]
	v_mfma_f32_16x16x32_bf16 v[72:75], v[156:159], v[240:243], v[72:75]
	v_mfma_f32_16x16x32_bf16 v[124:127], v[144:147], v[194:197], v[124:127]
	v_mfma_f32_16x16x32_bf16 v[120:123], v[160:163], v[194:197], v[120:123]
	v_mfma_f32_16x16x32_bf16 v[108:111], v[144:147], v[202:205], v[108:111]
	v_mfma_f32_16x16x32_bf16 v[104:107], v[160:163], v[202:205], v[104:107]
	v_mfma_f32_16x16x32_bf16 v[92:95], v[144:147], v[236:239], v[92:95]
	v_mfma_f32_16x16x32_bf16 v[88:91], v[160:163], v[236:239], v[88:91]
	v_mfma_f32_16x16x32_bf16 v[76:79], v[144:147], v[244:247], v[76:79]
	v_mfma_f32_16x16x32_bf16 v[72:75], v[160:163], v[244:247], v[72:75]
	s_setprio 0
	s_setprio 1
	v_mfma_f32_16x16x32_bf16 v[116:119], v[164:167], v[190:193], v[116:119]
	v_mfma_f32_16x16x32_bf16 v[112:115], v[182:185], v[190:193], v[112:115]
	v_mfma_f32_16x16x32_bf16 v[100:103], v[164:167], v[198:201], v[100:103]
	v_mfma_f32_16x16x32_bf16 v[96:99], v[182:185], v[198:201], v[96:99]
	v_mfma_f32_16x16x32_bf16 v[84:87], v[164:167], v[228:231], v[84:87]
	v_mfma_f32_16x16x32_bf16 v[80:83], v[182:185], v[228:231], v[80:83]
	v_mfma_f32_16x16x32_bf16 v[68:71], v[164:167], v[240:243], v[68:71]
	v_mfma_f32_16x16x32_bf16 v[64:67], v[182:185], v[240:243], v[64:67]
	v_mfma_f32_16x16x32_bf16 v[116:119], v[168:171], v[194:197], v[116:119]
	v_mfma_f32_16x16x32_bf16 v[112:115], v[186:189], v[194:197], v[112:115]
	v_mfma_f32_16x16x32_bf16 v[100:103], v[168:171], v[202:205], v[100:103]
	v_mfma_f32_16x16x32_bf16 v[96:99], v[186:189], v[202:205], v[96:99]
	s_setprio 2
	s_barrier
	v_mfma_f32_16x16x32_bf16 v[84:87], v[168:171], v[236:239], v[84:87]
	v_mfma_f32_16x16x32_bf16 v[80:83], v[186:189], v[236:239], v[80:83]
	v_mfma_f32_16x16x32_bf16 v[68:71], v[168:171], v[244:247], v[68:71]
	v_mfma_f32_16x16x32_bf16 v[64:67], v[186:189], v[244:247], v[64:67]
	s_setprio 0
	s_add_i32 s39, s39, s26
	v_lshl_add_u64 v[148:149], s[22:23], 0, v[130:131]
	s_mov_b32 m0, s39
	ds_read_b128 v[190:193], v154 offset:16384
	ds_read_b128 v[194:197], v154 offset:17408
	ds_read_b128 v[198:201], v154 offset:18432
	ds_read_b128 v[202:205], v154 offset:19456
	ds_read_b128 v[228:231], v154 offset:20480
	ds_read_b128 v[236:239], v154 offset:21504
	ds_read_b128 v[240:243], v154 offset:22528
	ds_read_b128 v[244:247], v154 offset:23552
	global_load_lds_dwordx4 v[148:149], off
	s_add_i32 m0, s39, 0x2000
	s_add_u32 s52, s22, 0x40000
	v_lshl_add_u64 v[206:207], s[22:23], 0, v[134:135]
	s_addc_u32 s53, s23, 0
	s_add_i32 s39, s45, s26
	global_load_lds_dwordx4 v[206:207], off
	v_lshl_add_u64 v[248:249], s[52:53], 0, v[130:131]
	s_mov_b32 m0, s39
	v_lshl_add_u64 v[250:251], s[24:25], 0, v[132:133]
	global_load_lds_dwordx4 v[248:249], off
	v_lshl_add_u64 v[248:249], s[52:53], 0, v[134:135]
	s_add_i32 m0, s39, 0x2000
	s_nop 0
	global_load_lds_dwordx4 v[248:249], off
	v_lshl_add_u64 v[248:249], s[24:25], 0, v[128:129]
	s_mov_b32 m0, s19
	s_nop 0
	global_load_lds_dwordx4 v[248:249], off
	s_mov_b32 m0, s27
	s_nop 0
	global_load_lds_dwordx4 v[250:251], off
	s_waitcnt vmcnt(8)
	s_waitcnt lgkmcnt(0)
	v_mfma_f32_16x16x32_bf16 v[60:63], v[140:143], v[190:193], v[60:63]
	v_mfma_f32_16x16x32_bf16 v[56:59], v[156:159], v[190:193], v[56:59]
	v_mfma_f32_16x16x32_bf16 v[44:47], v[140:143], v[198:201], v[44:47]
	v_mfma_f32_16x16x32_bf16 v[40:43], v[156:159], v[198:201], v[40:43]
	s_barrier
; #define PG8_STAGE(bufoff, gbase, voff) do { _Pragma("unroll") for (int _i = 0; _i < 2; ++_i) \
;         __builtin_amdgcn_global_load_lds((const unsigned*)((const char*)(gbase) + (voff)[_i]), (PG8_LAS unsigned*)(lds + (bufoff) + ldsw + _i * 8192), 16, 0, 0); } while (0)
; #define PG8_LDA(dst, b, h) do { _Pragma("unroll") for (int m = 0; m < 4; ++m) _Pragma("unroll") for (int k = 0; k < 2; ++k) dst[m][k] = *(const PG8_LAS bf16x8*)(lds + PG8_SA(b, h) + aoff + m * 2048 + k * 1024); } while (0)
; #define PG8_LDB(dst, b, h) do { _Pragma("unroll") for (int n = 0; n < 2; ++n) _Pragma("unroll") for (int k = 0; k < 2; ++k) dst[n][k] = *(const PG8_LAS bf16x8*)(lds + PG8_SB(b, h) + boff + n * 2048 + k * 1024); } while (0)
; #define PG8_MMA(ai, bj, At, Bt) do { __builtin_amdgcn_s_setprio(1); _Pragma("unroll") for (int m = 0; m < 4; ++m) _Pragma("unroll") for (int n = 0; n < 2; ++n) _Pragma("unroll") for (int k = 0; k < 2; ++k) \
;         acc[ai][bj][m][n] = __builtin_amdgcn_mfma_f32_16x16x32_bf16(Bt[n][k], At[m][k], acc[ai][bj][m][n], 0, 0, 0); __builtin_amdgcn_s_setprio(0); } while (0)
; #define PG8_WAIT_V(n) asm volatile("s_waitcnt vmcnt(" #n ")" ::: "memory")
; #define PG8_WAIT_L(n) asm volatile("s_waitcnt lgkmcnt(" #n ")" ::: "memory")
; #define PG8_BAR __builtin_amdgcn_s_barrier()
; #define PG8_SCHED __builtin_amdgcn_sched_barrier(0)
; template <class Epi, class Sched, bool ALIGN_EPI = false, bool SP2 = false>
; __device__ __forceinline__ void gemm_phase(PG8_LAS unsigned char* lds, const Gemm g, const Sched& S, const Epi& E) {
;     ...
;             PG8_WAIT_V(8); PG8_WAIT_L(0); PG8_BAR; PG8_MMA(1, 0, At, B0); PG8_MMA(1, 1, At, B1); PG8_BAR; PG8_SCHED;
;             PG8_LDB(B0, 1, 0); PG8_LDB(B1, 1, 1); PG8_SCHED; PG8_LDA(At, 1, 0); PG8_STAGE(PG8_SA(0, 1), a2 + hstep, voffA);
;             PG8_WAIT_V(8); PG8_WAIT_L(0); PG8_BAR; PG8_MMA(0, 0, At, B0); PG8_MMA(0, 1, At, B1); PG8_BAR; PG8_SCHED;
	s_setprio 1
	s_waitcnt lgkmcnt(0)
	v_mfma_f32_16x16x32_bf16 v[28:31], v[140:143], v[228:231], v[28:31]
	v_mfma_f32_16x16x32_bf16 v[24:27], v[156:159], v[228:231], v[24:27]
	v_mfma_f32_16x16x32_bf16 v[12:15], v[140:143], v[240:243], v[12:15]
	v_mfma_f32_16x16x32_bf16 v[8:11], v[156:159], v[240:243], v[8:11]
	v_mfma_f32_16x16x32_bf16 v[60:63], v[144:147], v[194:197], v[60:63]
	v_mfma_f32_16x16x32_bf16 v[56:59], v[160:163], v[194:197], v[56:59]
	v_mfma_f32_16x16x32_bf16 v[44:47], v[144:147], v[202:205], v[44:47]
	v_mfma_f32_16x16x32_bf16 v[40:43], v[160:163], v[202:205], v[40:43]
	v_mfma_f32_16x16x32_bf16 v[28:31], v[144:147], v[236:239], v[28:31]
	v_mfma_f32_16x16x32_bf16 v[24:27], v[160:163], v[236:239], v[24:27]
	v_mfma_f32_16x16x32_bf16 v[12:15], v[144:147], v[244:247], v[12:15]
	v_mfma_f32_16x16x32_bf16 v[8:11], v[160:163], v[244:247], v[8:11]
	s_setprio 0
	s_setprio 1
	v_mfma_f32_16x16x32_bf16 v[52:55], v[164:167], v[190:193], v[52:55]
	v_mfma_f32_16x16x32_bf16 v[48:51], v[182:185], v[190:193], v[48:51]
	v_mfma_f32_16x16x32_bf16 v[36:39], v[164:167], v[198:201], v[36:39]
	v_mfma_f32_16x16x32_bf16 v[32:35], v[182:185], v[198:201], v[32:35]
	v_mfma_f32_16x16x32_bf16 v[20:23], v[164:167], v[228:231], v[20:23]
	v_mfma_f32_16x16x32_bf16 v[16:19], v[182:185], v[228:231], v[16:19]
	v_mfma_f32_16x16x32_bf16 v[4:7], v[164:167], v[240:243], v[4:7]
	v_mfma_f32_16x16x32_bf16 v[0:3], v[182:185], v[240:243], v[0:3]
	v_mfma_f32_16x16x32_bf16 v[52:55], v[168:171], v[194:197], v[52:55]
	v_mfma_f32_16x16x32_bf16 v[48:51], v[186:189], v[194:197], v[48:51]
	v_mfma_f32_16x16x32_bf16 v[36:39], v[168:171], v[202:205], v[36:39]
	v_mfma_f32_16x16x32_bf16 v[32:35], v[186:189], v[202:205], v[32:35]
	s_setprio 2
	s_barrier
	v_mfma_f32_16x16x32_bf16 v[20:23], v[168:171], v[236:239], v[20:23]
	v_mfma_f32_16x16x32_bf16 v[16:19], v[186:189], v[236:239], v[16:19]
	v_mfma_f32_16x16x32_bf16 v[4:7], v[168:171], v[244:247], v[4:7]
	v_mfma_f32_16x16x32_bf16 v[0:3], v[186:189], v[244:247], v[0:3]
	s_setprio 0
	s_add_i32 s39, 0, 0x18000
	v_add_u32_e32 v155, s39, v151
	s_add_i32 s45, 0, 0x1c000
	ds_read_b128 v[140:143], v155
	ds_read_b128 v[144:147], v155 offset:1024
	ds_read_b128 v[156:159], v155 offset:2048
	ds_read_b128 v[160:163], v155 offset:3072
	v_add_u32_e32 v155, s45, v151
	ds_read_b128 v[164:167], v155
	ds_read_b128 v[168:171], v155 offset:1024
	ds_read_b128 v[182:185], v155 offset:2048
	ds_read_b128 v[186:189], v155 offset:3072
	s_add_u32 s24, s24, 0x40000
	s_addc_u32 s25, s25, 0
	s_mov_b32 m0, s28
	v_lshl_add_u64 v[210:211], s[24:25], 0, v[128:129]
	ds_read_b128 v[190:193], v154 offset:32768
	ds_read_b128 v[194:197], v154 offset:33792
	ds_read_b128 v[198:201], v154 offset:34816
	ds_read_b128 v[202:205], v154 offset:35840
	ds_read_b128 v[228:231], v154 offset:36864
	ds_read_b128 v[236:239], v154 offset:37888
	ds_read_b128 v[240:243], v154 offset:38912
	ds_read_b128 v[244:247], v154 offset:39936
	global_load_lds_dwordx4 v[210:211], off
	v_lshl_add_u64 v[210:211], s[24:25], 0, v[132:133]
	s_mov_b32 m0, s29
	s_nop 0
	global_load_lds_dwordx4 v[210:211], off
	s_waitcnt vmcnt(8)
	s_waitcnt lgkmcnt(0)
	v_mfma_f32_16x16x32_bf16 v[124:127], v[140:143], v[190:193], v[124:127]
	v_mfma_f32_16x16x32_bf16 v[120:123], v[156:159], v[190:193], v[120:123]
	v_mfma_f32_16x16x32_bf16 v[108:111], v[140:143], v[198:201], v[108:111]
	v_mfma_f32_16x16x32_bf16 v[104:107], v[156:159], v[198:201], v[104:107]
	s_barrier
	s_setprio 1
	s_waitcnt lgkmcnt(0)
	v_mfma_f32_16x16x32_bf16 v[92:95], v[140:143], v[228:231], v[92:95]
	v_mfma_f32_16x16x32_bf16 v[88:91], v[156:159], v[228:231], v[88:91]
	v_mfma_f32_16x16x32_bf16 v[76:79], v[140:143], v[240:243], v[76:79]
	v_mfma_f32_16x16x32_bf16 v[72:75], v[156:159], v[240:243], v[72:75]
	v_mfma_f32_16x16x32_bf16 v[124:127], v[144:147], v[194:197], v[124:127]
	v_mfma_f32_16x16x32_bf16 v[120:123], v[160:163], v[194:197], v[120:123]
	v_mfma_f32_16x16x32_bf16 v[108:111], v[144:147], v[202:205], v[108:111]
	v_mfma_f32_16x16x32_bf16 v[104:107], v[160:163], v[202:205], v[104:107]
	v_mfma_f32_16x16x32_bf16 v[92:95], v[144:147], v[236:239], v[92:95]
	v_mfma_f32_16x16x32_bf16 v[88:91], v[160:163], v[236:239], v[88:91]
	v_mfma_f32_16x16x32_bf16 v[76:79], v[144:147], v[244:247], v[76:79]
	v_mfma_f32_16x16x32_bf16 v[72:75], v[160:163], v[244:247], v[72:75]
	s_setprio 0
	s_setprio 1
	v_mfma_f32_16x16x32_bf16 v[116:119], v[164:167], v[190:193], v[116:119]
	v_mfma_f32_16x16x32_bf16 v[112:115], v[182:185], v[190:193], v[112:115]
	v_mfma_f32_16x16x32_bf16 v[100:103], v[164:167], v[198:201], v[100:103]
	v_mfma_f32_16x16x32_bf16 v[96:99], v[182:185], v[198:201], v[96:99]
	v_mfma_f32_16x16x32_bf16 v[84:87], v[164:167], v[228:231], v[84:87]
	v_mfma_f32_16x16x32_bf16 v[80:83], v[182:185], v[228:231], v[80:83]
	v_mfma_f32_16x16x32_bf16 v[68:71], v[164:167], v[240:243], v[68:71]
	v_mfma_f32_16x16x32_bf16 v[64:67], v[182:185], v[240:243], v[64:67]
	v_mfma_f32_16x16x32_bf16 v[116:119], v[168:171], v[194:197], v[116:119]
	v_mfma_f32_16x16x32_bf16 v[112:115], v[186:189], v[194:197], v[112:115]
	v_mfma_f32_16x16x32_bf16 v[100:103], v[168:171], v[202:205], v[100:103]
	v_mfma_f32_16x16x32_bf16 v[96:99], v[186:189], v[202:205], v[96:99]
	s_setprio 2
	s_barrier
; #define PG8_STAGE(bufoff, gbase, voff) do { _Pragma("unroll") for (int _i = 0; _i < 2; ++_i) \
;         __builtin_amdgcn_global_load_lds((const unsigned*)((const char*)(gbase) + (voff)[_i]), (PG8_LAS unsigned*)(lds + (bufoff) + ldsw + _i * 8192), 16, 0, 0); } while (0)
; #define PG8_LDA(dst, b, h) do { _Pragma("unroll") for (int m = 0; m < 4; ++m) _Pragma("unroll") for (int k = 0; k < 2; ++k) dst[m][k] = *(const PG8_LAS bf16x8*)(lds + PG8_SA(b, h) + aoff + m * 2048 + k * 1024); } while (0)
; #define PG8_MMA(ai, bj, At, Bt) do { __builtin_amdgcn_s_setprio(1); _Pragma("unroll") for (int m = 0; m < 4; ++m) _Pragma("unroll") for (int n = 0; n < 2; ++n) _Pragma("unroll") for (int k = 0; k < 2; ++k) \
;         acc[ai][bj][m][n] = __builtin_amdgcn_mfma_f32_16x16x32_bf16(Bt[n][k], At[m][k], acc[ai][bj][m][n], 0, 0, 0); __builtin_amdgcn_s_setprio(0); } while (0)
; #define PG8_WAIT_V(n) asm volatile("s_waitcnt vmcnt(" #n ")" ::: "memory")
; #define PG8_WAIT_L(n) asm volatile("s_waitcnt lgkmcnt(" #n ")" ::: "memory")
; #define PG8_BAR __builtin_amdgcn_s_barrier()
; #define PG8_SCHED __builtin_amdgcn_sched_barrier(0)
; template <class Epi, class Sched, bool ALIGN_EPI = false, bool SP2 = false>
; __device__ __forceinline__ void gemm_phase(PG8_LAS unsigned char* lds, const Gemm g, const Sched& S, const Epi& E) {
;     ...
;         for (int t = 0; t < nt; t += 2) {
;     ...
;             PG8_WAIT_V(8); PG8_WAIT_L(0); PG8_BAR; PG8_MMA(0, 0, At, B0); PG8_MMA(0, 1, At, B1); PG8_BAR; PG8_SCHED;
;             PG8_LDA(At, 1, 1); PG8_STAGE(PG8_SB(1, 0), b3, voffB); PG8_STAGE(PG8_SB(1, 1), b3 + hstep, voffB); PG8_STAGE(PG8_SA(1, 0), a3, voffA);
;             PG8_WAIT_V(8); PG8_WAIT_L(0); PG8_BAR; PG8_MMA(1, 0, At, B0); PG8_MMA(1, 1, At, B1); PG8_BAR; PG8_SCHED;
	v_mfma_f32_16x16x32_bf16 v[84:87], v[168:171], v[236:239], v[84:87]
	v_mfma_f32_16x16x32_bf16 v[80:83], v[186:189], v[236:239], v[80:83]
	v_mfma_f32_16x16x32_bf16 v[68:71], v[168:171], v[244:247], v[68:71]
	v_mfma_f32_16x16x32_bf16 v[64:67], v[186:189], v[244:247], v[64:67]
	s_setprio 0
	s_add_i32 s24, s39, s26
	v_lshl_add_u64 v[148:149], v[148:149], 0, s[88:89]
	s_mov_b32 m0, s24
	ds_read_b128 v[190:193], v154 offset:49152
	ds_read_b128 v[194:197], v154 offset:50176
	ds_read_b128 v[198:201], v154 offset:51200
	ds_read_b128 v[202:205], v154 offset:52224
	ds_read_b128 v[228:231], v154 offset:53248
	ds_read_b128 v[236:239], v154 offset:54272
	ds_read_b128 v[240:243], v154 offset:55296
	ds_read_b128 v[244:247], v154 offset:56320
	global_load_lds_dwordx4 v[148:149], off
	s_add_i32 m0, s24, 0x2000
	s_add_u32 s22, s22, 0x40080
	v_lshl_add_u64 v[148:149], v[206:207], 0, s[88:89]
	s_addc_u32 s23, s23, 0
	s_add_i32 s24, s45, s26
	global_load_lds_dwordx4 v[148:149], off
	v_lshl_add_u64 v[148:149], s[22:23], 0, v[130:131]
	s_mov_b32 m0, s24
	s_nop 0
	global_load_lds_dwordx4 v[148:149], off
	v_lshl_add_u64 v[148:149], s[22:23], 0, v[134:135]
	s_add_i32 m0, s24, 0x2000
	s_nop 0
	global_load_lds_dwordx4 v[148:149], off
	v_lshl_add_u64 v[148:149], v[248:249], 0, s[88:89]
	s_mov_b32 m0, s30
	s_nop 0
	global_load_lds_dwordx4 v[148:149], off
	v_lshl_add_u64 v[148:149], v[250:251], 0, s[88:89]
	s_mov_b32 m0, s31
	s_nop 0
	global_load_lds_dwordx4 v[148:149], off
	s_waitcnt vmcnt(8)
	s_waitcnt lgkmcnt(0)
	v_mfma_f32_16x16x32_bf16 v[60:63], v[140:143], v[190:193], v[60:63]
	v_mfma_f32_16x16x32_bf16 v[56:59], v[156:159], v[190:193], v[56:59]
	v_mfma_f32_16x16x32_bf16 v[44:47], v[140:143], v[198:201], v[44:47]
	v_mfma_f32_16x16x32_bf16 v[40:43], v[156:159], v[198:201], v[40:43]
	s_barrier
	s_setprio 1
	s_waitcnt lgkmcnt(0)
	v_mfma_f32_16x16x32_bf16 v[28:31], v[140:143], v[228:231], v[28:31]
	v_mfma_f32_16x16x32_bf16 v[24:27], v[156:159], v[228:231], v[24:27]
	v_mfma_f32_16x16x32_bf16 v[12:15], v[140:143], v[240:243], v[12:15]
	v_mfma_f32_16x16x32_bf16 v[8:11], v[156:159], v[240:243], v[8:11]
	v_mfma_f32_16x16x32_bf16 v[60:63], v[144:147], v[194:197], v[60:63]
	v_mfma_f32_16x16x32_bf16 v[56:59], v[160:163], v[194:197], v[56:59]
	v_mfma_f32_16x16x32_bf16 v[44:47], v[144:147], v[202:205], v[44:47]
	v_mfma_f32_16x16x32_bf16 v[40:43], v[160:163], v[202:205], v[40:43]
	v_mfma_f32_16x16x32_bf16 v[28:31], v[144:147], v[236:239], v[28:31]
	v_mfma_f32_16x16x32_bf16 v[24:27], v[160:163], v[236:239], v[24:27]
	v_mfma_f32_16x16x32_bf16 v[12:15], v[144:147], v[244:247], v[12:15]
	v_mfma_f32_16x16x32_bf16 v[8:11], v[160:163], v[244:247], v[8:11]
	s_setprio 0
	s_setprio 1
	v_mfma_f32_16x16x32_bf16 v[52:55], v[164:167], v[190:193], v[52:55]
	v_mfma_f32_16x16x32_bf16 v[48:51], v[182:185], v[190:193], v[48:51]
	v_mfma_f32_16x16x32_bf16 v[36:39], v[164:167], v[198:201], v[36:39]
	v_mfma_f32_16x16x32_bf16 v[32:35], v[182:185], v[198:201], v[32:35]
	v_mfma_f32_16x16x32_bf16 v[20:23], v[164:167], v[228:231], v[20:23]
	v_mfma_f32_16x16x32_bf16 v[16:19], v[182:185], v[228:231], v[16:19]
	v_mfma_f32_16x16x32_bf16 v[4:7], v[164:167], v[240:243], v[4:7]
	v_mfma_f32_16x16x32_bf16 v[0:3], v[182:185], v[240:243], v[0:3]
	v_mfma_f32_16x16x32_bf16 v[52:55], v[168:171], v[194:197], v[52:55]
	v_mfma_f32_16x16x32_bf16 v[48:51], v[186:189], v[194:197], v[48:51]
	v_mfma_f32_16x16x32_bf16 v[36:39], v[168:171], v[202:205], v[36:39]
	v_mfma_f32_16x16x32_bf16 v[32:35], v[186:189], v[202:205], v[32:35]
	s_setprio 2
	s_barrier
	v_mfma_f32_16x16x32_bf16 v[20:23], v[168:171], v[236:239], v[20:23]
	v_mfma_f32_16x16x32_bf16 v[16:19], v[186:189], v[236:239], v[16:19]
	v_mfma_f32_16x16x32_bf16 v[4:7], v[168:171], v[244:247], v[4:7]
	v_mfma_f32_16x16x32_bf16 v[0:3], v[186:189], v[244:247], v[0:3]
	s_setprio 0
	s_add_i32 s38, s38, 2
	s_add_u32 s20, s20, 0x100
	s_addc_u32 s21, s21, 0
	s_add_u32 s36, s36, 0x100
	s_addc_u32 s37, s37, 0
	s_cmp_gt_u32 s38, 13
	s_cbranch_scc0 .LBB0_274
	s_and_b64 vcc, exec, s[8:9]
	s_cbranch_vccz .LBB0_295
	s_barrier
	v_lshl_add_u32 v155, s4, 8, v150
	s_cmp_gt_i32 s18, 7
	s_mov_b64 s[4:5], -1
	s_cbranch_scc1 .LBB0_296

; #define PG8_STAGE(bufoff, gbase, voff) do { _Pragma("unroll") for (int _i = 0; _i < 2; ++_i) \
;         __builtin_amdgcn_global_load_lds((const unsigned*)((const char*)(gbase) + (voff)[_i]), (PG8_LAS unsigned*)(lds + (bufoff) + ldsw + _i * 8192), 16, 0, 0); } while (0)
; #define PG8_LDA(dst, b, h) do { _Pragma("unroll") for (int m = 0; m < 4; ++m) _Pragma("unroll") for (int k = 0; k < 2; ++k) dst[m][k] = *(const PG8_LAS bf16x8*)(lds + PG8_SA(b, h) + aoff + m * 2048 + k * 1024); } while (0)
; #define PG8_LDB(dst, b, h) do { _Pragma("unroll") for (int n = 0; n < 2; ++n) _Pragma("unroll") for (int k = 0; k < 2; ++k) dst[n][k] = *(const PG8_LAS bf16x8*)(lds + PG8_SB(b, h) + boff + n * 2048 + k * 1024); } while (0)
; #define PG8_MMA(ai, bj, At, Bt) do { __builtin_amdgcn_s_setprio(1); _Pragma("unroll") for (int m = 0; m < 4; ++m) _Pragma("unroll") for (int n = 0; n < 2; ++n) _Pragma("unroll") for (int k = 0; k < 2; ++k) \
;         acc[ai][bj][m][n] = __builtin_amdgcn_mfma_f32_16x16x32_bf16(Bt[n][k], At[m][k], acc[ai][bj][m][n], 0, 0, 0); __builtin_amdgcn_s_setprio(0); } while (0)
; #define PG8_WAIT_V(n) asm volatile("s_waitcnt vmcnt(" #n ")" ::: "memory")
; #define PG8_WAIT_L(n) asm volatile("s_waitcnt lgkmcnt(" #n ")" ::: "memory")
; #define PG8_BAR __builtin_amdgcn_s_barrier()
; #define PG8_SCHED __builtin_amdgcn_sched_barrier(0)
; template <class Epi, class Sched, bool ALIGN_EPI = false, bool SP2 = false>
; __device__ __forceinline__ void gemm_phase(PG8_LAS unsigned char* lds, const Gemm g, const Sched& S, const Epi& E) {
;     ...
;             PG8_LDB(B0, 0, 0); PG8_LDB(B1, 0, 1); PG8_SCHED; PG8_LDA(At, 0, 0); PG8_STAGE(PG8_SA(1, 1), a1 + hstep, voffA);
;             PG8_WAIT_V(8); PG8_WAIT_L(0); PG8_BAR; PG8_MMA(0, 0, At, B0); PG8_MMA(0, 1, At, B1); PG8_BAR; PG8_SCHED;
;             PG8_LDA(At, 0, 1); PG8_STAGE(PG8_SB(0, 0), b2, voffB); PG8_STAGE(PG8_SB(0, 1), b2 + hstep, voffB); PG8_STAGE(PG8_SA(0, 0), a2, voffA);
;             PG8_WAIT_V(8); PG8_WAIT_L(0); PG8_BAR; PG8_MMA(1, 0, At, B0); PG8_MMA(1, 1, At, B1); PG8_BAR; PG8_SCHED;
.LBB0_613:
	s_add_u32 s36, s34, 0xfffc0080
	s_addc_u32 s37, s35, -1
	s_add_i32 s68, 0, 0x10000
	s_cmp_eq_u32 s67, 12
	s_cselect_b32 s39, s27, s37
	s_cselect_b32 s38, s63, s36
	s_cselect_b32 s37, s25, s66
	s_cselect_b32 s36, s64, s65
	s_add_i32 s70, 0, 0x14000
	v_add_u32_e32 v84, s68, v228
	v_add_u32_e32 v156, s70, v228
	ds_read_b128 v[68:71], v84
	ds_read_b128 v[72:75], v84 offset:1024
	ds_read_b128 v[80:83], v84 offset:2048
	ds_read_b128 v[84:87], v84 offset:3072
	ds_read_b128 v[144:147], v156
	ds_read_b128 v[148:151], v156 offset:1024
	ds_read_b128 v[152:155], v156 offset:2048
	ds_read_b128 v[156:159], v156 offset:3072
	v_lshl_add_u64 v[210:211], s[34:35], 0, v[188:189]
	s_add_i32 m0, s52, 0xc000
	ds_read_b128 v[160:163], v230
	ds_read_b128 v[164:167], v230 offset:1024
	ds_read_b128 v[168:171], v230 offset:2048
	ds_read_b128 v[192:195], v230 offset:3072
	ds_read_b128 v[196:199], v230 offset:4096
	ds_read_b128 v[200:203], v230 offset:5120
	ds_read_b128 v[204:207], v230 offset:6144
	ds_read_b128 v[236:239], v230 offset:7168
	global_load_lds_dwordx4 v[210:211], off
	v_lshl_add_u64 v[210:211], s[34:35], 0, v[190:191]
	s_add_i32 m0, s52, 0xe000
	s_nop 0
	global_load_lds_dwordx4 v[210:211], off
	s_waitcnt vmcnt(8)
	s_waitcnt lgkmcnt(0)
	v_mfma_f32_16x16x32_bf16 v[140:143], v[68:71], v[160:163], v[140:143]
	v_mfma_f32_16x16x32_bf16 v[136:139], v[80:83], v[160:163], v[136:139]
	v_mfma_f32_16x16x32_bf16 v[124:127], v[68:71], v[168:171], v[124:127]
	v_mfma_f32_16x16x32_bf16 v[120:123], v[80:83], v[168:171], v[120:123]
	s_barrier
	s_setprio 1
	s_waitcnt lgkmcnt(0)
	v_mfma_f32_16x16x32_bf16 v[108:111], v[68:71], v[196:199], v[108:111]
	v_mfma_f32_16x16x32_bf16 v[104:107], v[80:83], v[196:199], v[104:107]
	v_mfma_f32_16x16x32_bf16 v[92:95], v[68:71], v[204:207], v[92:95]
	v_mfma_f32_16x16x32_bf16 v[88:91], v[80:83], v[204:207], v[88:91]
	v_mfma_f32_16x16x32_bf16 v[140:143], v[72:75], v[164:167], v[140:143]
	v_mfma_f32_16x16x32_bf16 v[136:139], v[84:87], v[164:167], v[136:139]
	v_mfma_f32_16x16x32_bf16 v[124:127], v[72:75], v[192:195], v[124:127]
	v_mfma_f32_16x16x32_bf16 v[120:123], v[84:87], v[192:195], v[120:123]
	v_mfma_f32_16x16x32_bf16 v[108:111], v[72:75], v[200:203], v[108:111]
	v_mfma_f32_16x16x32_bf16 v[104:107], v[84:87], v[200:203], v[104:107]
	v_mfma_f32_16x16x32_bf16 v[92:95], v[72:75], v[236:239], v[92:95]
	v_mfma_f32_16x16x32_bf16 v[88:91], v[84:87], v[236:239], v[88:91]
	s_setprio 0
	s_setprio 1
	v_mfma_f32_16x16x32_bf16 v[132:135], v[144:147], v[160:163], v[132:135]
	v_mfma_f32_16x16x32_bf16 v[128:131], v[152:155], v[160:163], v[128:131]
	v_mfma_f32_16x16x32_bf16 v[116:119], v[144:147], v[168:171], v[116:119]
	v_mfma_f32_16x16x32_bf16 v[112:115], v[152:155], v[168:171], v[112:115]
	v_mfma_f32_16x16x32_bf16 v[100:103], v[144:147], v[196:199], v[100:103]
	v_mfma_f32_16x16x32_bf16 v[96:99], v[152:155], v[196:199], v[96:99]
	v_mfma_f32_16x16x32_bf16 v[76:79], v[144:147], v[204:207], v[76:79]
	v_mfma_f32_16x16x32_bf16 v[64:67], v[152:155], v[204:207], v[64:67]
	v_mfma_f32_16x16x32_bf16 v[132:135], v[148:151], v[164:167], v[132:135]
	v_mfma_f32_16x16x32_bf16 v[128:131], v[156:159], v[164:167], v[128:131]
	v_mfma_f32_16x16x32_bf16 v[116:119], v[148:151], v[192:195], v[116:119]
	v_mfma_f32_16x16x32_bf16 v[112:115], v[156:159], v[192:195], v[112:115]
	s_setprio 2
	s_barrier
	v_mfma_f32_16x16x32_bf16 v[100:103], v[148:151], v[200:203], v[100:103]
	v_mfma_f32_16x16x32_bf16 v[96:99], v[156:159], v[200:203], v[96:99]
	v_mfma_f32_16x16x32_bf16 v[76:79], v[148:151], v[236:239], v[76:79]
	v_mfma_f32_16x16x32_bf16 v[64:67], v[156:159], v[236:239], v[64:67]
	s_setprio 0
	s_add_i32 s68, s68, s45
	v_lshl_add_u64 v[210:211], s[36:37], 0, v[172:173]
	s_mov_b32 m0, s68
	ds_read_b128 v[160:163], v230 offset:16384
	ds_read_b128 v[164:167], v230 offset:17408
	ds_read_b128 v[168:171], v230 offset:18432
	ds_read_b128 v[192:195], v230 offset:19456
	ds_read_b128 v[196:199], v230 offset:20480
	ds_read_b128 v[200:203], v230 offset:21504
	ds_read_b128 v[204:207], v230 offset:22528
	ds_read_b128 v[236:239], v230 offset:23552
	global_load_lds_dwordx4 v[210:211], off
	s_add_i32 m0, s68, 0x2000
	s_add_u32 s68, s36, 0x40000
	v_lshl_add_u64 v[240:241], s[36:37], 0, v[182:183]
	s_addc_u32 s69, s37, 0
	s_add_i32 s70, s70, s45
	global_load_lds_dwordx4 v[240:241], off
	v_lshl_add_u64 v[242:243], s[68:69], 0, v[172:173]
	s_mov_b32 m0, s70
	v_lshl_add_u64 v[244:245], s[38:39], 0, v[184:185]
	global_load_lds_dwordx4 v[242:243], off
	v_lshl_add_u64 v[242:243], s[68:69], 0, v[182:183]
	s_add_i32 m0, s70, 0x2000
	s_nop 0
	global_load_lds_dwordx4 v[242:243], off
	v_lshl_add_u64 v[242:243], s[38:39], 0, v[186:187]
	s_mov_b32 m0, s52
	s_nop 0
	global_load_lds_dwordx4 v[242:243], off
	s_mov_b32 m0, s53
	s_nop 0
	global_load_lds_dwordx4 v[244:245], off
	s_waitcnt vmcnt(8)
	s_waitcnt lgkmcnt(0)
	v_mfma_f32_16x16x32_bf16 v[60:63], v[68:71], v[160:163], v[60:63]
	v_mfma_f32_16x16x32_bf16 v[56:59], v[80:83], v[160:163], v[56:59]
	v_mfma_f32_16x16x32_bf16 v[44:47], v[68:71], v[168:171], v[44:47]
	v_mfma_f32_16x16x32_bf16 v[40:43], v[80:83], v[168:171], v[40:43]
	s_barrier
; #define PG8_STAGE(bufoff, gbase, voff) do { _Pragma("unroll") for (int _i = 0; _i < 2; ++_i) \
;         __builtin_amdgcn_global_load_lds((const unsigned*)((const char*)(gbase) + (voff)[_i]), (PG8_LAS unsigned*)(lds + (bufoff) + ldsw + _i * 8192), 16, 0, 0); } while (0)
; #define PG8_LDA(dst, b, h) do { _Pragma("unroll") for (int m = 0; m < 4; ++m) _Pragma("unroll") for (int k = 0; k < 2; ++k) dst[m][k] = *(const PG8_LAS bf16x8*)(lds + PG8_SA(b, h) + aoff + m * 2048 + k * 1024); } while (0)
; #define PG8_LDB(dst, b, h) do { _Pragma("unroll") for (int n = 0; n < 2; ++n) _Pragma("unroll") for (int k = 0; k < 2; ++k) dst[n][k] = *(const PG8_LAS bf16x8*)(lds + PG8_SB(b, h) + boff + n * 2048 + k * 1024); } while (0)
; #define PG8_MMA(ai, bj, At, Bt) do { __builtin_amdgcn_s_setprio(1); _Pragma("unroll") for (int m = 0; m < 4; ++m) _Pragma("unroll") for (int n = 0; n < 2; ++n) _Pragma("unroll") for (int k = 0; k < 2; ++k) \
;         acc[ai][bj][m][n] = __builtin_amdgcn_mfma_f32_16x16x32_bf16(Bt[n][k], At[m][k], acc[ai][bj][m][n], 0, 0, 0); __builtin_amdgcn_s_setprio(0); } while (0)
; #define PG8_WAIT_V(n) asm volatile("s_waitcnt vmcnt(" #n ")" ::: "memory")
; #define PG8_WAIT_L(n) asm volatile("s_waitcnt lgkmcnt(" #n ")" ::: "memory")
; #define PG8_BAR __builtin_amdgcn_s_barrier()
; #define PG8_SCHED __builtin_amdgcn_sched_barrier(0)
; template <class Epi, class Sched, bool ALIGN_EPI = false, bool SP2 = false>
; __device__ __forceinline__ void gemm_phase(PG8_LAS unsigned char* lds, const Gemm g, const Sched& S, const Epi& E) {
;     ...
;             PG8_WAIT_V(8); PG8_WAIT_L(0); PG8_BAR; PG8_MMA(1, 0, At, B0); PG8_MMA(1, 1, At, B1); PG8_BAR; PG8_SCHED;
;             PG8_LDB(B0, 1, 0); PG8_LDB(B1, 1, 1); PG8_SCHED; PG8_LDA(At, 1, 0); PG8_STAGE(PG8_SA(0, 1), a2 + hstep, voffA);
;             PG8_WAIT_V(8); PG8_WAIT_L(0); PG8_BAR; PG8_MMA(0, 0, At, B0); PG8_MMA(0, 1, At, B1); PG8_BAR; PG8_SCHED;
	s_setprio 1
	s_waitcnt lgkmcnt(0)
	v_mfma_f32_16x16x32_bf16 v[28:31], v[68:71], v[196:199], v[28:31]
	v_mfma_f32_16x16x32_bf16 v[24:27], v[80:83], v[196:199], v[24:27]
	v_mfma_f32_16x16x32_bf16 v[12:15], v[68:71], v[204:207], v[12:15]
	v_mfma_f32_16x16x32_bf16 v[8:11], v[80:83], v[204:207], v[8:11]
	v_mfma_f32_16x16x32_bf16 v[60:63], v[72:75], v[164:167], v[60:63]
	v_mfma_f32_16x16x32_bf16 v[56:59], v[84:87], v[164:167], v[56:59]
	v_mfma_f32_16x16x32_bf16 v[44:47], v[72:75], v[192:195], v[44:47]
	v_mfma_f32_16x16x32_bf16 v[40:43], v[84:87], v[192:195], v[40:43]
	v_mfma_f32_16x16x32_bf16 v[28:31], v[72:75], v[200:203], v[28:31]
	v_mfma_f32_16x16x32_bf16 v[24:27], v[84:87], v[200:203], v[24:27]
	v_mfma_f32_16x16x32_bf16 v[12:15], v[72:75], v[236:239], v[12:15]
	v_mfma_f32_16x16x32_bf16 v[8:11], v[84:87], v[236:239], v[8:11]
	s_setprio 0
	s_setprio 1
	v_mfma_f32_16x16x32_bf16 v[52:55], v[144:147], v[160:163], v[52:55]
	v_mfma_f32_16x16x32_bf16 v[48:51], v[152:155], v[160:163], v[48:51]
	v_mfma_f32_16x16x32_bf16 v[36:39], v[144:147], v[168:171], v[36:39]
	v_mfma_f32_16x16x32_bf16 v[32:35], v[152:155], v[168:171], v[32:35]
	v_mfma_f32_16x16x32_bf16 v[20:23], v[144:147], v[196:199], v[20:23]
	v_mfma_f32_16x16x32_bf16 v[16:19], v[152:155], v[196:199], v[16:19]
	v_mfma_f32_16x16x32_bf16 v[4:7], v[144:147], v[204:207], v[4:7]
	v_mfma_f32_16x16x32_bf16 v[0:3], v[152:155], v[204:207], v[0:3]
	v_mfma_f32_16x16x32_bf16 v[52:55], v[148:151], v[164:167], v[52:55]
	v_mfma_f32_16x16x32_bf16 v[48:51], v[156:159], v[164:167], v[48:51]
	v_mfma_f32_16x16x32_bf16 v[36:39], v[148:151], v[192:195], v[36:39]
	v_mfma_f32_16x16x32_bf16 v[32:35], v[156:159], v[192:195], v[32:35]
	s_setprio 2
	s_barrier
	v_mfma_f32_16x16x32_bf16 v[20:23], v[148:151], v[200:203], v[20:23]
	v_mfma_f32_16x16x32_bf16 v[16:19], v[156:159], v[200:203], v[16:19]
	v_mfma_f32_16x16x32_bf16 v[4:7], v[148:151], v[236:239], v[4:7]
	v_mfma_f32_16x16x32_bf16 v[0:3], v[156:159], v[236:239], v[0:3]
	s_setprio 0
	s_add_i32 s68, 0, 0x18000
	s_add_i32 s69, 0, 0x1c000
	v_add_u32_e32 v84, s68, v228
	v_add_u32_e32 v156, s69, v228
	ds_read_b128 v[68:71], v84
	ds_read_b128 v[72:75], v84 offset:1024
	ds_read_b128 v[80:83], v84 offset:2048
	ds_read_b128 v[84:87], v84 offset:3072
	ds_read_b128 v[144:147], v156
	ds_read_b128 v[148:151], v156 offset:1024
	ds_read_b128 v[152:155], v156 offset:2048
	ds_read_b128 v[156:159], v156 offset:3072
	s_add_u32 s38, s38, 0x40000
	s_addc_u32 s39, s39, 0
	s_mov_b32 m0, s54
	v_lshl_add_u64 v[246:247], s[38:39], 0, v[186:187]
	ds_read_b128 v[160:163], v230 offset:32768
	ds_read_b128 v[164:167], v230 offset:33792
	ds_read_b128 v[168:171], v230 offset:34816
	ds_read_b128 v[192:195], v230 offset:35840
	ds_read_b128 v[196:199], v230 offset:36864
	ds_read_b128 v[200:203], v230 offset:37888
	ds_read_b128 v[204:207], v230 offset:38912
	ds_read_b128 v[236:239], v230 offset:39936
	global_load_lds_dwordx4 v[246:247], off
	v_lshl_add_u64 v[246:247], s[38:39], 0, v[184:185]
	s_mov_b32 m0, s55
	s_nop 0
	global_load_lds_dwordx4 v[246:247], off
	s_waitcnt vmcnt(8)
	s_waitcnt lgkmcnt(0)
	v_mfma_f32_16x16x32_bf16 v[140:143], v[68:71], v[160:163], v[140:143]
	v_mfma_f32_16x16x32_bf16 v[136:139], v[80:83], v[160:163], v[136:139]
	v_mfma_f32_16x16x32_bf16 v[124:127], v[68:71], v[168:171], v[124:127]
	v_mfma_f32_16x16x32_bf16 v[120:123], v[80:83], v[168:171], v[120:123]
	s_barrier
	s_setprio 1
	s_waitcnt lgkmcnt(0)
	v_mfma_f32_16x16x32_bf16 v[108:111], v[68:71], v[196:199], v[108:111]
	v_mfma_f32_16x16x32_bf16 v[104:107], v[80:83], v[196:199], v[104:107]
	v_mfma_f32_16x16x32_bf16 v[92:95], v[68:71], v[204:207], v[92:95]
	v_mfma_f32_16x16x32_bf16 v[88:91], v[80:83], v[204:207], v[88:91]
	v_mfma_f32_16x16x32_bf16 v[140:143], v[72:75], v[164:167], v[140:143]
	v_mfma_f32_16x16x32_bf16 v[136:139], v[84:87], v[164:167], v[136:139]
	v_mfma_f32_16x16x32_bf16 v[124:127], v[72:75], v[192:195], v[124:127]
	v_mfma_f32_16x16x32_bf16 v[120:123], v[84:87], v[192:195], v[120:123]
	v_mfma_f32_16x16x32_bf16 v[108:111], v[72:75], v[200:203], v[108:111]
	v_mfma_f32_16x16x32_bf16 v[104:107], v[84:87], v[200:203], v[104:107]
	v_mfma_f32_16x16x32_bf16 v[92:95], v[72:75], v[236:239], v[92:95]
	v_mfma_f32_16x16x32_bf16 v[88:91], v[84:87], v[236:239], v[88:91]
	s_setprio 0
	s_setprio 1
	v_mfma_f32_16x16x32_bf16 v[132:135], v[144:147], v[160:163], v[132:135]
	v_mfma_f32_16x16x32_bf16 v[128:131], v[152:155], v[160:163], v[128:131]
	v_mfma_f32_16x16x32_bf16 v[116:119], v[144:147], v[168:171], v[116:119]
	v_mfma_f32_16x16x32_bf16 v[112:115], v[152:155], v[168:171], v[112:115]
	v_mfma_f32_16x16x32_bf16 v[100:103], v[144:147], v[196:199], v[100:103]
	v_mfma_f32_16x16x32_bf16 v[96:99], v[152:155], v[196:199], v[96:99]
	v_mfma_f32_16x16x32_bf16 v[76:79], v[144:147], v[204:207], v[76:79]
	v_mfma_f32_16x16x32_bf16 v[64:67], v[152:155], v[204:207], v[64:67]
	v_mfma_f32_16x16x32_bf16 v[132:135], v[148:151], v[164:167], v[132:135]
	v_mfma_f32_16x16x32_bf16 v[128:131], v[156:159], v[164:167], v[128:131]
	v_mfma_f32_16x16x32_bf16 v[116:119], v[148:151], v[192:195], v[116:119]
	v_mfma_f32_16x16x32_bf16 v[112:115], v[156:159], v[192:195], v[112:115]
	s_setprio 2
	s_barrier
; #define PG8_STAGE(bufoff, gbase, voff) do { _Pragma("unroll") for (int _i = 0; _i < 2; ++_i) \
;         __builtin_amdgcn_global_load_lds((const unsigned*)((const char*)(gbase) + (voff)[_i]), (PG8_LAS unsigned*)(lds + (bufoff) + ldsw + _i * 8192), 16, 0, 0); } while (0)
; #define PG8_LDA(dst, b, h) do { _Pragma("unroll") for (int m = 0; m < 4; ++m) _Pragma("unroll") for (int k = 0; k < 2; ++k) dst[m][k] = *(const PG8_LAS bf16x8*)(lds + PG8_SA(b, h) + aoff + m * 2048 + k * 1024); } while (0)
; #define PG8_MMA(ai, bj, At, Bt) do { __builtin_amdgcn_s_setprio(1); _Pragma("unroll") for (int m = 0; m < 4; ++m) _Pragma("unroll") for (int n = 0; n < 2; ++n) _Pragma("unroll") for (int k = 0; k < 2; ++k) \
;         acc[ai][bj][m][n] = __builtin_amdgcn_mfma_f32_16x16x32_bf16(Bt[n][k], At[m][k], acc[ai][bj][m][n], 0, 0, 0); __builtin_amdgcn_s_setprio(0); } while (0)
; #define PG8_WAIT_V(n) asm volatile("s_waitcnt vmcnt(" #n ")" ::: "memory")
; #define PG8_WAIT_L(n) asm volatile("s_waitcnt lgkmcnt(" #n ")" ::: "memory")
; #define PG8_BAR __builtin_amdgcn_s_barrier()
; #define PG8_SCHED __builtin_amdgcn_sched_barrier(0)
; template <class Epi, class Sched, bool ALIGN_EPI = false, bool SP2 = false>
; __device__ __forceinline__ void gemm_phase(PG8_LAS unsigned char* lds, const Gemm g, const Sched& S, const Epi& E) {
;     ...
;         for (int t = 0; t < nt; t += 2) {
;     ...
;             PG8_WAIT_V(8); PG8_WAIT_L(0); PG8_BAR; PG8_MMA(0, 0, At, B0); PG8_MMA(0, 1, At, B1); PG8_BAR; PG8_SCHED;
;             PG8_LDA(At, 1, 1); PG8_STAGE(PG8_SB(1, 0), b3, voffB); PG8_STAGE(PG8_SB(1, 1), b3 + hstep, voffB); PG8_STAGE(PG8_SA(1, 0), a3, voffA);
;             PG8_WAIT_V(8); PG8_WAIT_L(0); PG8_BAR; PG8_MMA(1, 0, At, B0); PG8_MMA(1, 1, At, B1); PG8_BAR; PG8_SCHED;
	v_mfma_f32_16x16x32_bf16 v[100:103], v[148:151], v[200:203], v[100:103]
	v_mfma_f32_16x16x32_bf16 v[96:99], v[156:159], v[200:203], v[96:99]
	v_mfma_f32_16x16x32_bf16 v[76:79], v[148:151], v[236:239], v[76:79]
	v_mfma_f32_16x16x32_bf16 v[64:67], v[156:159], v[236:239], v[64:67]
	s_setprio 0
	s_add_i32 s38, s68, s45
	v_lshl_add_u64 v[210:211], v[210:211], 0, s[88:89]
	s_mov_b32 m0, s38
	ds_read_b128 v[160:163], v230 offset:49152
	ds_read_b128 v[164:167], v230 offset:50176
	ds_read_b128 v[168:171], v230 offset:51200
	ds_read_b128 v[192:195], v230 offset:52224
	ds_read_b128 v[196:199], v230 offset:53248
	ds_read_b128 v[200:203], v230 offset:54272
	ds_read_b128 v[204:207], v230 offset:55296
	ds_read_b128 v[236:239], v230 offset:56320
	global_load_lds_dwordx4 v[210:211], off
	s_add_i32 m0, s38, 0x2000
	s_add_u32 s36, s36, 0x40080
	v_lshl_add_u64 v[210:211], v[240:241], 0, s[88:89]
	s_addc_u32 s37, s37, 0
	s_add_i32 s38, s69, s45
	global_load_lds_dwordx4 v[210:211], off
	v_lshl_add_u64 v[210:211], s[36:37], 0, v[172:173]
	s_mov_b32 m0, s38
	s_nop 0
	global_load_lds_dwordx4 v[210:211], off
	v_lshl_add_u64 v[210:211], s[36:37], 0, v[182:183]
	s_add_i32 m0, s38, 0x2000
	s_nop 0
	global_load_lds_dwordx4 v[210:211], off
	v_lshl_add_u64 v[210:211], v[242:243], 0, s[88:89]
	s_mov_b32 m0, s56
	s_nop 0
	global_load_lds_dwordx4 v[210:211], off
	v_lshl_add_u64 v[210:211], v[244:245], 0, s[88:89]
	s_mov_b32 m0, s57
	s_nop 0
	global_load_lds_dwordx4 v[210:211], off
	s_waitcnt vmcnt(8)
	s_waitcnt lgkmcnt(0)
	v_mfma_f32_16x16x32_bf16 v[60:63], v[68:71], v[160:163], v[60:63]
	v_mfma_f32_16x16x32_bf16 v[56:59], v[80:83], v[160:163], v[56:59]
	v_mfma_f32_16x16x32_bf16 v[44:47], v[68:71], v[168:171], v[44:47]
	v_mfma_f32_16x16x32_bf16 v[40:43], v[80:83], v[168:171], v[40:43]
	s_barrier
	s_setprio 1
	s_waitcnt lgkmcnt(0)
	v_mfma_f32_16x16x32_bf16 v[28:31], v[68:71], v[196:199], v[28:31]
	v_mfma_f32_16x16x32_bf16 v[24:27], v[80:83], v[196:199], v[24:27]
	v_mfma_f32_16x16x32_bf16 v[12:15], v[68:71], v[204:207], v[12:15]
	v_mfma_f32_16x16x32_bf16 v[8:11], v[80:83], v[204:207], v[8:11]
	v_mfma_f32_16x16x32_bf16 v[60:63], v[72:75], v[164:167], v[60:63]
	v_mfma_f32_16x16x32_bf16 v[56:59], v[84:87], v[164:167], v[56:59]
	v_mfma_f32_16x16x32_bf16 v[44:47], v[72:75], v[192:195], v[44:47]
	v_mfma_f32_16x16x32_bf16 v[40:43], v[84:87], v[192:195], v[40:43]
	v_mfma_f32_16x16x32_bf16 v[28:31], v[72:75], v[200:203], v[28:31]
	v_mfma_f32_16x16x32_bf16 v[24:27], v[84:87], v[200:203], v[24:27]
	v_mfma_f32_16x16x32_bf16 v[12:15], v[72:75], v[236:239], v[12:15]
	v_mfma_f32_16x16x32_bf16 v[8:11], v[84:87], v[236:239], v[8:11]
	s_setprio 0
	s_setprio 1
	v_mfma_f32_16x16x32_bf16 v[52:55], v[144:147], v[160:163], v[52:55]
	v_mfma_f32_16x16x32_bf16 v[48:51], v[152:155], v[160:163], v[48:51]
	v_mfma_f32_16x16x32_bf16 v[36:39], v[144:147], v[168:171], v[36:39]
	v_mfma_f32_16x16x32_bf16 v[32:35], v[152:155], v[168:171], v[32:35]
	v_mfma_f32_16x16x32_bf16 v[20:23], v[144:147], v[196:199], v[20:23]
	v_mfma_f32_16x16x32_bf16 v[16:19], v[152:155], v[196:199], v[16:19]
	v_mfma_f32_16x16x32_bf16 v[4:7], v[144:147], v[204:207], v[4:7]
	v_mfma_f32_16x16x32_bf16 v[0:3], v[152:155], v[204:207], v[0:3]
	v_mfma_f32_16x16x32_bf16 v[52:55], v[148:151], v[164:167], v[52:55]
	v_mfma_f32_16x16x32_bf16 v[48:51], v[156:159], v[164:167], v[48:51]
	v_mfma_f32_16x16x32_bf16 v[36:39], v[148:151], v[192:195], v[36:39]
	v_mfma_f32_16x16x32_bf16 v[32:35], v[156:159], v[192:195], v[32:35]
	s_setprio 2
	s_barrier
	v_mfma_f32_16x16x32_bf16 v[20:23], v[148:151], v[200:203], v[20:23]
	v_mfma_f32_16x16x32_bf16 v[16:19], v[156:159], v[200:203], v[16:19]
	v_mfma_f32_16x16x32_bf16 v[4:7], v[148:151], v[236:239], v[4:7]
	v_mfma_f32_16x16x32_bf16 v[0:3], v[156:159], v[236:239], v[0:3]
	s_setprio 0
	s_add_i32 s67, s67, 2
	s_add_u32 s34, s34, 0x100
	s_addc_u32 s35, s35, 0
	s_add_u32 s65, s65, 0x100
	s_addc_u32 s66, s66, 0
	s_cmp_gt_u32 s67, 13
	s_cbranch_scc0 .LBB0_613
	s_and_b64 vcc, exec, s[22:23]
	s_cbranch_vccz .LBB0_616
	s_barrier
